# even layer: workgroups whose wave 0 carries an extra context-query attention unit hand their context-DFT slab to the neighbour workgroup bx+8 (plus the bias moves of the previous version)
# speedup vs baseline: 1.0106x; 1.0026x over previous
.LBB0_447:
	s_waitcnt lgkmcnt(0)
	s_load_dwordx2 s[6:7], s[82:83], 0xb0
	s_waitcnt vmcnt(6)
	v_cndmask_b32_e64 v0, 0, 1, s[4:5]
	v_cmp_ne_u32_e64 s[8:9], 1, v0
	s_andn2_b64 vcc, exec, s[4:5]
	s_nop 0
	v_writelane_b32 v254, s8, 4
	s_nop 1
	v_writelane_b32 v254, s9, 5
	s_cbranch_vccnz .LBB0_454
	v_mbcnt_lo_u32_b32 v0, -1, 0
	v_mbcnt_hi_u32_b32 v0, -1, v0
	v_add_u32_e32 v0, s72, v0
	v_cvt_f32_i32_e32 v1, v0
	v_mul_f32_e32 v1, 0x3b800000, v1
	v_cos_f32_e32 v2, v1
	v_sin_f32_e32 v3, v1
	s_waitcnt lgkmcnt(0)
	s_add_u32 s4, s6, 0x9600000
	s_addc_u32 s5, s7, 0
	s_add_u32 s6, s6, 0xc100000
	s_addc_u32 s7, s7, 0
	v_lshrrev_b32_e32 v4, 7, v0
	v_bfe_u32 v5, v0, 3, 4
	v_and_b32_e32 v6, 7, v0
	v_lshlrev_b32_e32 v7, 7, v6
	v_lshlrev_b32_e32 v8, 11, v4
	v_lshl_add_u32 v8, v5, 3, v8
	v_lshl_add_u32 v9, v4, 4, v5
	v_mul_u32_u24_e32 v9, 0x88, v9
	v_lshl_add_u32 v10, v4, 4, v6
	v_mul_u32_u24_e32 v10, 0x88, v10
	v_lshl_add_u32 v10, v5, 3, v10
	v_mul_u32_u24_e32 v11, v5, v6
	v_lshlrev_b32_e32 v12, 3, v5
	v_add_u32_e32 v12, v11, v12
	v_lshlrev_b32_e32 v11, 3, v11
	v_lshlrev_b32_e32 v12, 3, v12
	v_lshl_add_u32 v13, v6, 4, v5
	v_lshl_add_u32 v13, v4, 8, v13
	v_lshlrev_b32_e32 v13, 3, v13
	v_lshrrev_b32_e32 v14, 1, v0
	v_and_b32_e32 v15, 1, v0
	v_sub_u32_e32 v44, 0x100, v14
	v_and_b32_e32 v44, 0xff, v44
	v_lshlrev_b32_e32 v45, 12, v15
	v_lshl_add_u32 v46, v14, 3, v45
	v_lshl_add_u32 v47, v44, 3, v45
	s_mov_b32 s2, s93
	s_mov_b32 s94, s74
	s_movk_i32 s95, 0xff
	s_and_b64 s[14:15], s[10:11], exec
	s_cbranch_scc0 .Lcd_slab
	s_cmp_lg_u32 s74, 0x100
	s_cbranch_scc1 .Lcd_slab
	s_bitcmp0_b32 s93, 3
	s_cbranch_scc1 .LBB0_454
	s_add_i32 s2, s93, -8
	s_movk_i32 s94, 8
	s_mov_b32 s95, s93

.Lcd_ld_done:
	s_or_b64 exec, exec, s[14:15]
	s_waitcnt lgkmcnt(0)
	s_barrier
	v_mov_b32_e32 v32, 0
	v_mov_b32_e32 v33, 0
	v_mov_b32_e32 v34, 0
	v_mov_b32_e32 v35, 0
	v_mov_b32_e32 v36, 0
	v_add_u32_e32 v37, v36, v7
	v_and_b32_e32 v37, 0x780, v37
	v_add_u32_e32 v38, v37, v7
	v_and_b32_e32 v38, 0x780, v38
	v_add_u32_e32 v39, v38, v7
	v_and_b32_e32 v39, 0x780, v39
	ds_read_b64 v[16:17], v8
	ds_read_b64 v[24:25], v36 offset:8192
	ds_read_b64 v[18:19], v8 offset:128
	ds_read_b64 v[26:27], v37 offset:8192
	ds_read_b64 v[20:21], v8 offset:256
	ds_read_b64 v[28:29], v38 offset:8192
	ds_read_b64 v[22:23], v8 offset:384
	ds_read_b64 v[30:31], v39 offset:8192
	s_waitcnt lgkmcnt(0)
	v_fma_f32 v32, v16, v24, v32
	v_fma_f32 v33, v17, v24, v33
	v_fma_f32 v32, v17, v25, v32
	v_fma_f32 v33, -v16, v25, v33
	v_fma_f32 v34, v18, v26, v34
	v_fma_f32 v35, v19, v26, v35
	v_fma_f32 v34, v19, v27, v34
	v_fma_f32 v35, -v18, v27, v35
	v_fma_f32 v32, v20, v28, v32
	v_fma_f32 v33, v21, v28, v33
	v_fma_f32 v32, v21, v29, v32
	v_fma_f32 v33, -v20, v29, v33
	v_fma_f32 v34, v22, v30, v34
	v_fma_f32 v35, v23, v30, v35
	v_fma_f32 v34, v23, v31, v34
	v_fma_f32 v35, -v22, v31, v35
	v_add_u32_e32 v36, v39, v7
	v_and_b32_e32 v36, 0x780, v36
	v_add_u32_e32 v37, v36, v7
	v_and_b32_e32 v37, 0x780, v37
	v_add_u32_e32 v38, v37, v7
	v_and_b32_e32 v38, 0x780, v38
	v_add_u32_e32 v39, v38, v7
	v_and_b32_e32 v39, 0x780, v39
	ds_read_b64 v[16:17], v8 offset:512
	ds_read_b64 v[24:25], v36 offset:8192
	ds_read_b64 v[18:19], v8 offset:640
	ds_read_b64 v[26:27], v37 offset:8192
	ds_read_b64 v[20:21], v8 offset:768
	ds_read_b64 v[28:29], v38 offset:8192
	ds_read_b64 v[22:23], v8 offset:896
	ds_read_b64 v[30:31], v39 offset:8192
	s_waitcnt lgkmcnt(0)
	v_fma_f32 v32, v16, v24, v32
	v_fma_f32 v33, v17, v24, v33
	v_fma_f32 v32, v17, v25, v32
	v_fma_f32 v33, -v16, v25, v33
	v_fma_f32 v34, v18, v26, v34
	v_fma_f32 v35, v19, v26, v35
	v_fma_f32 v34, v19, v27, v34
	v_fma_f32 v35, -v18, v27, v35
	v_fma_f32 v32, v20, v28, v32
	v_fma_f32 v33, v21, v28, v33
	v_fma_f32 v32, v21, v29, v32
	v_fma_f32 v33, -v20, v29, v33
	v_fma_f32 v34, v22, v30, v34
	v_fma_f32 v35, v23, v30, v35
	v_fma_f32 v34, v23, v31, v34
	v_fma_f32 v35, -v22, v31, v35
	v_add_u32_e32 v36, v39, v7
	v_and_b32_e32 v36, 0x780, v36
	v_add_u32_e32 v37, v36, v7
	v_and_b32_e32 v37, 0x780, v37
	v_add_u32_e32 v38, v37, v7
	v_and_b32_e32 v38, 0x780, v38
	v_add_u32_e32 v39, v38, v7
	v_and_b32_e32 v39, 0x780, v39
	ds_read_b64 v[16:17], v8 offset:1024
	ds_read_b64 v[24:25], v36 offset:8192
	ds_read_b64 v[18:19], v8 offset:1152
	ds_read_b64 v[26:27], v37 offset:8192
	ds_read_b64 v[20:21], v8 offset:1280
	ds_read_b64 v[28:29], v38 offset:8192
	ds_read_b64 v[22:23], v8 offset:1408
	ds_read_b64 v[30:31], v39 offset:8192
	s_waitcnt lgkmcnt(0)
	v_fma_f32 v32, v16, v24, v32
	v_fma_f32 v33, v17, v24, v33
	v_fma_f32 v32, v17, v25, v32
	v_fma_f32 v33, -v16, v25, v33
	v_fma_f32 v34, v18, v26, v34
	v_fma_f32 v35, v19, v26, v35
	v_fma_f32 v34, v19, v27, v34
	v_fma_f32 v35, -v18, v27, v35
	v_fma_f32 v32, v20, v28, v32
	v_fma_f32 v33, v21, v28, v33
	v_fma_f32 v32, v21, v29, v32
	v_fma_f32 v33, -v20, v29, v33
	v_fma_f32 v34, v22, v30, v34
	v_fma_f32 v35, v23, v30, v35
	v_fma_f32 v34, v23, v31, v34
	v_fma_f32 v35, -v22, v31, v35
	v_add_u32_e32 v36, v39, v7
	v_and_b32_e32 v36, 0x780, v36
	v_add_u32_e32 v37, v36, v7
	v_and_b32_e32 v37, 0x780, v37
	v_add_u32_e32 v38, v37, v7
	v_and_b32_e32 v38, 0x780, v38
	v_add_u32_e32 v39, v38, v7
	v_and_b32_e32 v39, 0x780, v39
	ds_read_b64 v[16:17], v8 offset:1536
	ds_read_b64 v[24:25], v36 offset:8192
	ds_read_b64 v[18:19], v8 offset:1664
	ds_read_b64 v[26:27], v37 offset:8192
	ds_read_b64 v[20:21], v8 offset:1792
	ds_read_b64 v[28:29], v38 offset:8192
	ds_read_b64 v[22:23], v8 offset:1920
	ds_read_b64 v[30:31], v39 offset:8192
	s_waitcnt lgkmcnt(0)
	v_fma_f32 v32, v16, v24, v32
	v_fma_f32 v33, v17, v24, v33
	v_fma_f32 v32, v17, v25, v32
	v_fma_f32 v33, -v16, v25, v33
	v_fma_f32 v34, v18, v26, v34
	v_fma_f32 v35, v19, v26, v35
	v_fma_f32 v34, v19, v27, v34
	v_fma_f32 v35, -v18, v27, v35
	v_fma_f32 v32, v20, v28, v32
	v_fma_f32 v33, v21, v28, v33
	v_fma_f32 v32, v21, v29, v32
	v_fma_f32 v33, -v20, v29, v33
	v_fma_f32 v34, v22, v30, v34
	v_fma_f32 v35, v23, v30, v35
	v_fma_f32 v34, v23, v31, v34
	v_fma_f32 v35, -v22, v31, v35
	v_add_f32_e32 v40, v32, v34
	v_add_f32_e32 v41, v33, v35
	v_sub_f32_e32 v42, v32, v34
	v_sub_f32_e32 v43, v33, v35
	ds_read_b64 v[24:25], v11 offset:8192
	ds_read_b64 v[26:27], v12 offset:8192
	s_waitcnt lgkmcnt(0)
	v_mul_f32_e32 v20, v40, v24
	v_mul_f32_e32 v21, v41, v24
	v_mul_f32_e32 v22, v42, v26
	v_mul_f32_e32 v23, v43, v26
	v_fma_f32 v20, v41, v25, v20
	v_fma_f32 v21, -v40, v25, v21
	v_fma_f32 v22, v43, v27, v22
	v_fma_f32 v23, -v42, v27, v23
	ds_write_b64 v10, v[20:21] offset:12288
	ds_write_b64 v10, v[22:23] offset:13376
	s_waitcnt lgkmcnt(0)
	s_barrier
	v_add_u32_e32 v50, 0x3000, v9
	v_mov_b32_e32 v32, 0
	v_mov_b32_e32 v33, 0
	v_mov_b32_e32 v34, 0
	v_mov_b32_e32 v35, 0
	v_mov_b32_e32 v36, 0
	v_add_u32_e32 v37, v36, v7
	v_and_b32_e32 v37, 0x780, v37
	v_add_u32_e32 v38, v37, v7
	v_and_b32_e32 v38, 0x780, v38
	v_add_u32_e32 v39, v38, v7
	v_and_b32_e32 v39, 0x780, v39
	ds_read_b64 v[16:17], v50
	ds_read_b64 v[24:25], v36 offset:8192
	ds_read_b64 v[18:19], v50 offset:8
	ds_read_b64 v[26:27], v37 offset:8192
	ds_read_b64 v[20:21], v50 offset:16
	ds_read_b64 v[28:29], v38 offset:8192
	ds_read_b64 v[22:23], v50 offset:24
	ds_read_b64 v[30:31], v39 offset:8192
	s_waitcnt lgkmcnt(0)
	v_fma_f32 v32, v16, v24, v32
	v_fma_f32 v33, v17, v24, v33
	v_fma_f32 v32, v17, v25, v32
	v_fma_f32 v33, -v16, v25, v33
	v_fma_f32 v34, v18, v26, v34
	v_fma_f32 v35, v19, v26, v35
	v_fma_f32 v34, v19, v27, v34
	v_fma_f32 v35, -v18, v27, v35
	v_fma_f32 v32, v20, v28, v32
	v_fma_f32 v33, v21, v28, v33
	v_fma_f32 v32, v21, v29, v32
	v_fma_f32 v33, -v20, v29, v33
	v_fma_f32 v34, v22, v30, v34
	v_fma_f32 v35, v23, v30, v35
	v_fma_f32 v34, v23, v31, v34
	v_fma_f32 v35, -v22, v31, v35
	v_add_u32_e32 v36, v39, v7
	v_and_b32_e32 v36, 0x780, v36
	v_add_u32_e32 v37, v36, v7
	v_and_b32_e32 v37, 0x780, v37
	v_add_u32_e32 v38, v37, v7
	v_and_b32_e32 v38, 0x780, v38
	v_add_u32_e32 v39, v38, v7
	v_and_b32_e32 v39, 0x780, v39
	ds_read_b64 v[16:17], v50 offset:32
	ds_read_b64 v[24:25], v36 offset:8192
	ds_read_b64 v[18:19], v50 offset:40
	ds_read_b64 v[26:27], v37 offset:8192
	ds_read_b64 v[20:21], v50 offset:48
	ds_read_b64 v[28:29], v38 offset:8192
	ds_read_b64 v[22:23], v50 offset:56
	ds_read_b64 v[30:31], v39 offset:8192
	s_waitcnt lgkmcnt(0)
	v_fma_f32 v32, v16, v24, v32
	v_fma_f32 v33, v17, v24, v33
	v_fma_f32 v32, v17, v25, v32
	v_fma_f32 v33, -v16, v25, v33
	v_fma_f32 v34, v18, v26, v34
	v_fma_f32 v35, v19, v26, v35
	v_fma_f32 v34, v19, v27, v34
	v_fma_f32 v35, -v18, v27, v35
	v_fma_f32 v32, v20, v28, v32
	v_fma_f32 v33, v21, v28, v33
	v_fma_f32 v32, v21, v29, v32
	v_fma_f32 v33, -v20, v29, v33
	v_fma_f32 v34, v22, v30, v34
	v_fma_f32 v35, v23, v30, v35
	v_fma_f32 v34, v23, v31, v34
	v_fma_f32 v35, -v22, v31, v35
	v_add_u32_e32 v36, v39, v7
	v_and_b32_e32 v36, 0x780, v36
	v_add_u32_e32 v37, v36, v7
	v_and_b32_e32 v37, 0x780, v37
	v_add_u32_e32 v38, v37, v7
	v_and_b32_e32 v38, 0x780, v38
	v_add_u32_e32 v39, v38, v7
	v_and_b32_e32 v39, 0x780, v39
	ds_read_b64 v[16:17], v50 offset:64
	ds_read_b64 v[24:25], v36 offset:8192
	ds_read_b64 v[18:19], v50 offset:72
	ds_read_b64 v[26:27], v37 offset:8192
	ds_read_b64 v[20:21], v50 offset:80
	ds_read_b64 v[28:29], v38 offset:8192
	ds_read_b64 v[22:23], v50 offset:88
	ds_read_b64 v[30:31], v39 offset:8192
	s_waitcnt lgkmcnt(0)
	v_fma_f32 v32, v16, v24, v32
	v_fma_f32 v33, v17, v24, v33
	v_fma_f32 v32, v17, v25, v32
	v_fma_f32 v33, -v16, v25, v33
	v_fma_f32 v34, v18, v26, v34
	v_fma_f32 v35, v19, v26, v35
	v_fma_f32 v34, v19, v27, v34
	v_fma_f32 v35, -v18, v27, v35
	v_fma_f32 v32, v20, v28, v32
	v_fma_f32 v33, v21, v28, v33
	v_fma_f32 v32, v21, v29, v32
	v_fma_f32 v33, -v20, v29, v33
	v_fma_f32 v34, v22, v30, v34
	v_fma_f32 v35, v23, v30, v35
	v_fma_f32 v34, v23, v31, v34
	v_fma_f32 v35, -v22, v31, v35
	v_add_u32_e32 v36, v39, v7
	v_and_b32_e32 v36, 0x780, v36
	v_add_u32_e32 v37, v36, v7
	v_and_b32_e32 v37, 0x780, v37
	v_add_u32_e32 v38, v37, v7
	v_and_b32_e32 v38, 0x780, v38
	v_add_u32_e32 v39, v38, v7
	v_and_b32_e32 v39, 0x780, v39
	ds_read_b64 v[16:17], v50 offset:96
	ds_read_b64 v[24:25], v36 offset:8192
	ds_read_b64 v[18:19], v50 offset:104
	ds_read_b64 v[26:27], v37 offset:8192
	ds_read_b64 v[20:21], v50 offset:112
	ds_read_b64 v[28:29], v38 offset:8192
	ds_read_b64 v[22:23], v50 offset:120
	ds_read_b64 v[30:31], v39 offset:8192
	s_waitcnt lgkmcnt(0)
	v_fma_f32 v32, v16, v24, v32
	v_fma_f32 v33, v17, v24, v33
	v_fma_f32 v32, v17, v25, v32
	v_fma_f32 v33, -v16, v25, v33
	v_fma_f32 v34, v18, v26, v34
	v_fma_f32 v35, v19, v26, v35
	v_fma_f32 v34, v19, v27, v34
	v_fma_f32 v35, -v18, v27, v35
	v_fma_f32 v32, v20, v28, v32
	v_fma_f32 v33, v21, v28, v33
	v_fma_f32 v32, v21, v29, v32
	v_fma_f32 v33, -v20, v29, v33
	v_fma_f32 v34, v22, v30, v34
	v_fma_f32 v35, v23, v30, v35
	v_fma_f32 v34, v23, v31, v34
	v_fma_f32 v35, -v22, v31, v35
	v_add_f32_e32 v40, v32, v34
	v_add_f32_e32 v41, v33, v35
	v_sub_f32_e32 v42, v32, v34
	v_sub_f32_e32 v43, v33, v35
	ds_write_b64 v13, v[40:41] offset:24576
	ds_write_b64 v13, v[42:43] offset:25600
	s_waitcnt lgkmcnt(0)
	s_barrier
	ds_read_b64 v[16:17], v46 offset:24576
	ds_read_b64 v[18:19], v47 offset:24576
	ds_read_b64 v[20:21], v46 offset:26624
	ds_read_b64 v[22:23], v47 offset:26624
	v_add_u32_e32 v48, s16, v14
	v_mul_u32_u24_e32 v48, 0xc00, v48
	v_add_u32_e32 v48, s8, v48
	v_lshl_add_u32 v48, v15, 3, v48
	s_waitcnt lgkmcnt(0)
	v_add_f32_e32 v24, v16, v18
	v_add_f32_e32 v25, v17, v19
	v_sub_f32_e32 v26, v17, v19
	v_sub_f32_e32 v27, v18, v16
	v_add_f32_e32 v28, v20, v22
	v_add_f32_e32 v29, v21, v23
	v_sub_f32_e32 v30, v21, v23
	v_sub_f32_e32 v31, v22, v20
	v_mul_f32_e32 v24, 0x3d000000, v24
	v_mul_f32_e32 v25, 0x3d000000, v25
	v_mul_f32_e32 v26, 0x3d000000, v26
	v_mul_f32_e32 v27, 0x3d000000, v27
	v_mul_f32_e32 v28, 0x3d000000, v28
	v_mul_f32_e32 v29, 0x3d000000, v29
	v_mul_f32_e32 v30, 0x3d000000, v30
	v_mul_f32_e32 v31, 0x3d000000, v31
	s_nop 0
	v_cvt_pk_bf16_f32 v32, v24, v25
	v_cvt_pk_bf16_f32 v33, v28, v29
	v_cvt_pk_bf16_f32 v34, v26, v27
	v_cvt_pk_bf16_f32 v35, v30, v31
	global_store_dwordx2 v48, v[32:33], s[6:7]
	global_store_dwordx2 v48, v[34:35], s[6:7] offset:1024
	s_add_i32 s2, s2, s94
	s_cmp_gt_i32 s2, s95
	s_barrier
	s_cbranch_scc0 .Lcd_slab
